# P1 balance: cumulative-gate scan rewritten by hand (coalesced gather/scatter through LDS, same scan arithmetic) and the kmax row pass moved off the 16 scan blocks; on top of v9
# speedup vs baseline: 1.0123x; 1.0123x over previous
.LBB0_334:
	s_or_b64 exec, exec, s[12:13]
	v_readlane_b32 s0, v252, 16
	v_readlane_b32 s1, v252, 17
	s_andn2_b64 vcc, exec, s[0:1]
	s_waitcnt lgkmcnt(0)
	s_barrier
	s_cbranch_vccnz .LBB0_390
	v_mov_b32_e32 v20, v136
	v_and_b32_e32 v21, 63, v136
	v_lshrrev_b32_e32 v22, 6, v136
	v_readlane_b32 s0, v249, 6
	v_readlane_b32 s12, v252, 18
	v_readlane_b32 s13, v252, 19
	v_readlane_b32 s36, v252, 22
	v_readlane_b32 s37, v252, 23
	v_lshlrev_b32_e32 v23, 5, v20
	s_lshl_b32 s0, s0, 5
	s_nop 2
	v_add_u32_e32 v23, s0, v23
	global_load_dword v40, v23, s[12:13]
	v_add_u32_e32 v24, 0x4000, v23
	global_load_dword v41, v24, s[12:13]
	v_add_u32_e32 v24, 0x8000, v23
	global_load_dword v42, v24, s[12:13]
	v_add_u32_e32 v24, 0xc000, v23
	global_load_dword v43, v24, s[12:13]
	v_add_u32_e32 v24, 0x10000, v23
	global_load_dword v44, v24, s[12:13]
	v_add_u32_e32 v24, 0x14000, v23
	global_load_dword v45, v24, s[12:13]
	v_add_u32_e32 v24, 0x18000, v23
	global_load_dword v46, v24, s[12:13]
	v_add_u32_e32 v24, 0x1c000, v23
	global_load_dword v47, v24, s[12:13]
	v_add_u32_e32 v24, 0x20000, v23
	global_load_dword v48, v24, s[12:13]
	v_add_u32_e32 v24, 0x24000, v23
	global_load_dword v49, v24, s[12:13]
	v_add_u32_e32 v24, 0x28000, v23
	global_load_dword v50, v24, s[12:13]
	v_add_u32_e32 v24, 0x2c000, v23
	global_load_dword v51, v24, s[12:13]
	v_add_u32_e32 v24, 0x30000, v23
	global_load_dword v52, v24, s[12:13]
	v_add_u32_e32 v24, 0x34000, v23
	global_load_dword v53, v24, s[12:13]
	v_add_u32_e32 v24, 0x38000, v23
	global_load_dword v54, v24, s[12:13]
	v_add_u32_e32 v24, 0x3c000, v23
	global_load_dword v55, v24, s[12:13]
	v_cmp_gt_u32_e32 vcc, 0x80, v20
	v_add_u32_e32 v24, 0x40000, v23
	s_nop 0
	v_cndmask_b32_e32 v24, v23, v24, vcc
	global_load_dword v56, v24, s[12:13]
	v_lshlrev_b32_e32 v25, 2, v20
	v_add_u32_e32 v25, 0x400, v25
	s_waitcnt vmcnt(16)
	ds_write_b32 v25, v40 offset:0
	s_waitcnt vmcnt(15)
	ds_write_b32 v25, v41 offset:2048
	s_waitcnt vmcnt(14)
	ds_write_b32 v25, v42 offset:4096
	s_waitcnt vmcnt(13)
	ds_write_b32 v25, v43 offset:6144
	s_waitcnt vmcnt(12)
	ds_write_b32 v25, v44 offset:8192
	s_waitcnt vmcnt(11)
	ds_write_b32 v25, v45 offset:10240
	s_waitcnt vmcnt(10)
	ds_write_b32 v25, v46 offset:12288
	s_waitcnt vmcnt(9)
	ds_write_b32 v25, v47 offset:14336
	s_waitcnt vmcnt(8)
	ds_write_b32 v25, v48 offset:16384
	s_waitcnt vmcnt(7)
	ds_write_b32 v25, v49 offset:18432
	s_waitcnt vmcnt(6)
	ds_write_b32 v25, v50 offset:20480
	s_waitcnt vmcnt(5)
	ds_write_b32 v25, v51 offset:22528
	s_waitcnt vmcnt(4)
	ds_write_b32 v25, v52 offset:24576
	s_waitcnt vmcnt(3)
	ds_write_b32 v25, v53 offset:26624
	s_waitcnt vmcnt(2)
	ds_write_b32 v25, v54 offset:28672
	s_waitcnt vmcnt(1)
	ds_write_b32 v25, v55 offset:30720
	s_waitcnt vmcnt(0)
	v_cndmask_b32_e32 v56, 0, v56, vcc
	ds_write_b32 v25, v56 offset:32768
	s_waitcnt lgkmcnt(0)
	s_barrier
	v_mul_u32_u24_e32 v26, 0x44, v20
	v_add_u32_e32 v31, 0x8c00, v26
	v_add_u32_e32 v26, 0x400, v26
	ds_read_b32 v40, v26 offset:0
	ds_read_b32 v41, v26 offset:4
	ds_read_b32 v42, v26 offset:8
	ds_read_b32 v43, v26 offset:12
	ds_read_b32 v44, v26 offset:16
	ds_read_b32 v45, v26 offset:20
	ds_read_b32 v46, v26 offset:24
	ds_read_b32 v47, v26 offset:28
	ds_read_b32 v48, v26 offset:32
	ds_read_b32 v49, v26 offset:36
	ds_read_b32 v50, v26 offset:40
	ds_read_b32 v51, v26 offset:44
	ds_read_b32 v52, v26 offset:48
	ds_read_b32 v53, v26 offset:52
	ds_read_b32 v54, v26 offset:56
	ds_read_b32 v55, v26 offset:60
	ds_read_b32 v56, v26 offset:64
	s_waitcnt lgkmcnt(0)
	v_add_f32_e32 v40, 0, v40
	v_add_f32_e32 v41, v40, v41
	v_add_f32_e32 v42, v41, v42
	v_add_f32_e32 v43, v42, v43
	v_add_f32_e32 v44, v43, v44
	v_add_f32_e32 v45, v44, v45
	v_add_f32_e32 v46, v45, v46
	v_add_f32_e32 v47, v46, v47
	v_add_f32_e32 v48, v47, v48
	v_add_f32_e32 v49, v48, v49
	v_add_f32_e32 v50, v49, v50
	v_add_f32_e32 v51, v50, v51
	v_add_f32_e32 v52, v51, v52
	v_add_f32_e32 v53, v52, v53
	v_add_f32_e32 v54, v53, v54
	v_add_f32_e32 v55, v54, v55
	v_add_f32_e32 v56, v55, v56
	v_mov_b32_e32 v27, v56
	v_subrev_u32_e32 v28, 1, v21
	v_lshlrev_b32_e32 v28, 2, v28
	ds_bpermute_b32 v28, v28, v27
	v_cmp_le_u32_e32 vcc, 1, v21
	s_waitcnt lgkmcnt(0)
	v_add_f32_e32 v29, v27, v28
	s_nop 0
	v_cndmask_b32_e32 v27, v27, v29, vcc
	v_subrev_u32_e32 v28, 2, v21
	v_lshlrev_b32_e32 v28, 2, v28
	ds_bpermute_b32 v28, v28, v27
	v_cmp_le_u32_e32 vcc, 2, v21
	s_waitcnt lgkmcnt(0)
	v_add_f32_e32 v29, v27, v28
	s_nop 0
	v_cndmask_b32_e32 v27, v27, v29, vcc
	v_subrev_u32_e32 v28, 4, v21
	v_lshlrev_b32_e32 v28, 2, v28
	ds_bpermute_b32 v28, v28, v27
	v_cmp_le_u32_e32 vcc, 4, v21
	s_waitcnt lgkmcnt(0)
	v_add_f32_e32 v29, v27, v28
	s_nop 0
	v_cndmask_b32_e32 v27, v27, v29, vcc
	v_subrev_u32_e32 v28, 8, v21
	v_lshlrev_b32_e32 v28, 2, v28
	ds_bpermute_b32 v28, v28, v27
	v_cmp_le_u32_e32 vcc, 8, v21
	s_waitcnt lgkmcnt(0)
	v_add_f32_e32 v29, v27, v28
	s_nop 0
	v_cndmask_b32_e32 v27, v27, v29, vcc
	v_subrev_u32_e32 v28, 16, v21
	v_lshlrev_b32_e32 v28, 2, v28
	ds_bpermute_b32 v28, v28, v27
	v_cmp_le_u32_e32 vcc, 16, v21
	s_waitcnt lgkmcnt(0)
	v_add_f32_e32 v29, v27, v28
	s_nop 0
	v_cndmask_b32_e32 v27, v27, v29, vcc
	v_subrev_u32_e32 v28, 32, v21
	v_lshlrev_b32_e32 v28, 2, v28
	ds_bpermute_b32 v28, v28, v27
	v_cmp_le_u32_e32 vcc, 32, v21
	s_waitcnt lgkmcnt(0)
	v_add_f32_e32 v29, v27, v28
	s_nop 0
	v_cndmask_b32_e32 v27, v27, v29, vcc
	v_cmp_eq_u32_e32 vcc, 63, v21
	v_lshlrev_b32_e32 v28, 2, v22
	s_and_saveexec_b64 s[0:1], vcc
	ds_write_b32 v28, v27
	s_mov_b64 exec, s[0:1]
	s_waitcnt lgkmcnt(0)
	s_barrier
	ds_read_b128 v[60:63], v139
	ds_read_b128 v[64:67], v139 offset:16
	v_sub_f32_e32 v30, v27, v56
	s_waitcnt lgkmcnt(0)
	v_cmp_lt_u32_e32 vcc, 0, v22
	s_nop 1
	v_cndmask_b32_e32 v32, 0, v60, vcc
	v_add_f32_e32 v30, v30, v32
	v_cmp_lt_u32_e32 vcc, 1, v22
	s_nop 1
	v_cndmask_b32_e32 v32, 0, v61, vcc
	v_add_f32_e32 v30, v30, v32
	v_cmp_lt_u32_e32 vcc, 2, v22
	s_nop 1
	v_cndmask_b32_e32 v32, 0, v62, vcc
	v_add_f32_e32 v30, v30, v32
	v_cmp_lt_u32_e32 vcc, 3, v22
	s_nop 1
	v_cndmask_b32_e32 v32, 0, v63, vcc
	v_add_f32_e32 v30, v30, v32
	v_cmp_lt_u32_e32 vcc, 4, v22
	s_nop 1
	v_cndmask_b32_e32 v32, 0, v64, vcc
	v_add_f32_e32 v30, v30, v32
	v_cmp_lt_u32_e32 vcc, 5, v22
	s_nop 1
	v_cndmask_b32_e32 v32, 0, v65, vcc
	v_add_f32_e32 v30, v30, v32
	v_cmp_lt_u32_e32 vcc, 6, v22
	s_nop 1
	v_cndmask_b32_e32 v32, 0, v66, vcc
	v_add_f32_e32 v30, v30, v32
	v_cmp_lt_u32_e32 vcc, 7, v22
	s_nop 1
	v_cndmask_b32_e32 v32, 0, v67, vcc
	v_add_f32_e32 v30, v30, v32
	v_add_f32_e32 v40, v40, v30
	ds_write_b32 v31, v40 offset:0
	v_add_f32_e32 v41, v41, v30
	ds_write_b32 v31, v41 offset:4
	v_add_f32_e32 v42, v42, v30
	ds_write_b32 v31, v42 offset:8
	v_add_f32_e32 v43, v43, v30
	ds_write_b32 v31, v43 offset:12
	v_add_f32_e32 v44, v44, v30
	ds_write_b32 v31, v44 offset:16
	v_add_f32_e32 v45, v45, v30
	ds_write_b32 v31, v45 offset:20
	v_add_f32_e32 v46, v46, v30
	ds_write_b32 v31, v46 offset:24
	v_add_f32_e32 v47, v47, v30
	ds_write_b32 v31, v47 offset:28
	v_add_f32_e32 v48, v48, v30
	ds_write_b32 v31, v48 offset:32
	v_add_f32_e32 v49, v49, v30
	ds_write_b32 v31, v49 offset:36
	v_add_f32_e32 v50, v50, v30
	ds_write_b32 v31, v50 offset:40
	v_add_f32_e32 v51, v51, v30
	ds_write_b32 v31, v51 offset:44
	v_add_f32_e32 v52, v52, v30
	ds_write_b32 v31, v52 offset:48
	v_add_f32_e32 v53, v53, v30
	ds_write_b32 v31, v53 offset:52
	v_add_f32_e32 v54, v54, v30
	ds_write_b32 v31, v54 offset:56
	v_add_f32_e32 v55, v55, v30
	ds_write_b32 v31, v55 offset:60
	v_add_f32_e32 v56, v56, v30
	ds_write_b32 v31, v56 offset:64
	s_waitcnt lgkmcnt(0)
	s_barrier
	v_lshlrev_b32_e32 v25, 2, v20
	v_add_u32_e32 v25, 0x8c00, v25
	ds_read_b32 v40, v25 offset:0
	ds_read_b32 v41, v25 offset:2048
	ds_read_b32 v42, v25 offset:4096
	ds_read_b32 v43, v25 offset:6144
	ds_read_b32 v44, v25 offset:8192
	ds_read_b32 v45, v25 offset:10240
	ds_read_b32 v46, v25 offset:12288
	ds_read_b32 v47, v25 offset:14336
	ds_read_b32 v48, v25 offset:16384
	ds_read_b32 v49, v25 offset:18432
	ds_read_b32 v50, v25 offset:20480
	ds_read_b32 v51, v25 offset:22528
	ds_read_b32 v52, v25 offset:24576
	ds_read_b32 v53, v25 offset:26624
	ds_read_b32 v54, v25 offset:28672
	ds_read_b32 v55, v25 offset:30720
	ds_read_b32 v56, v25 offset:32768
	v_lshlrev_b32_e32 v23, 2, v20
	s_waitcnt lgkmcnt(15)
	global_store_dword v23, v40, s[36:37]
	s_waitcnt lgkmcnt(15)
	v_add_u32_e32 v24, 0x800, v23
	global_store_dword v24, v41, s[36:37]
	s_waitcnt lgkmcnt(14)
	v_add_u32_e32 v24, 0x1000, v23
	global_store_dword v24, v42, s[36:37]
	s_waitcnt lgkmcnt(13)
	v_add_u32_e32 v24, 0x1800, v23
	global_store_dword v24, v43, s[36:37]
	s_waitcnt lgkmcnt(12)
	v_add_u32_e32 v24, 0x2000, v23
	global_store_dword v24, v44, s[36:37]
	s_waitcnt lgkmcnt(11)
	v_add_u32_e32 v24, 0x2800, v23
	global_store_dword v24, v45, s[36:37]
	s_waitcnt lgkmcnt(10)
	v_add_u32_e32 v24, 0x3000, v23
	global_store_dword v24, v46, s[36:37]
	s_waitcnt lgkmcnt(9)
	v_add_u32_e32 v24, 0x3800, v23
	global_store_dword v24, v47, s[36:37]
	s_waitcnt lgkmcnt(8)
	v_add_u32_e32 v24, 0x4000, v23
	global_store_dword v24, v48, s[36:37]
	s_waitcnt lgkmcnt(7)
	v_add_u32_e32 v24, 0x4800, v23
	global_store_dword v24, v49, s[36:37]
	s_waitcnt lgkmcnt(6)
	v_add_u32_e32 v24, 0x5000, v23
	global_store_dword v24, v50, s[36:37]
	s_waitcnt lgkmcnt(5)
	v_add_u32_e32 v24, 0x5800, v23
	global_store_dword v24, v51, s[36:37]
	s_waitcnt lgkmcnt(4)
	v_add_u32_e32 v24, 0x6000, v23
	global_store_dword v24, v52, s[36:37]
	s_waitcnt lgkmcnt(3)
	v_add_u32_e32 v24, 0x6800, v23
	global_store_dword v24, v53, s[36:37]
	s_waitcnt lgkmcnt(2)
	v_add_u32_e32 v24, 0x7000, v23
	global_store_dword v24, v54, s[36:37]
	s_waitcnt lgkmcnt(1)
	v_add_u32_e32 v24, 0x7800, v23
	global_store_dword v24, v55, s[36:37]
	v_readfirstlane_b32 s0, v22
	s_waitcnt lgkmcnt(0)
	s_cmp_lt_u32 s0, 2
	s_cbranch_scc0 .Lcum_nolast
	v_add_u32_e32 v24, 0x8000, v23
	global_store_dword v24, v56, s[36:37]

.LBB0_365:
.LBB0_366:
.LBB0_367:
.LBB0_390:
	s_mov_b32 s100, s82
	s_mov_b32 s101, s14
	s_cmp_lg_u32 s96, 0x100
	s_cbranch_scc1 .Lkmax_go
	s_add_i32 s100, s82, 0xffffff80
	s_movk_i32 s101, 0x780
	s_cmp_lt_u32 s2, 16
	s_cselect_b32 s100, 0x4100, s100
.Lkmax_go:
	v_mov_b32_e32 v36, v136
	v_mov_b32_e32 v52, 0
	v_ashrrev_i32_e32 v40, 6, v36
	v_add_u32_e32 v54, s100, v40
	v_and_b32_e32 v37, 63, v36
	v_cmp_gt_i32_e32 vcc, s23, v54
	v_mov_b32_e32 v53, 0
	s_and_saveexec_b64 s[12:13], vcc
	s_cbranch_execz .LBB0_410
	v_and_b32_e32 v1, 64, v183
	v_xor_b32_e32 v0, 1, v183
	v_add_u32_e32 v1, 64, v1
	v_cmp_lt_i32_e32 vcc, v0, v1
	v_lshlrev_b32_e32 v138, 4, v37
	v_lshl_add_u64 v[38:39], s[6:7], 0, v[138:139]
	v_cndmask_b32_e32 v0, v183, v0, vcc
	v_lshlrev_b32_e32 v41, 2, v0
	v_xor_b32_e32 v0, 2, v183
	v_cmp_lt_i32_e32 vcc, v0, v1
	v_mov_b32_e32 v52, 0
	s_mov_b64 s[36:37], 0
	v_cndmask_b32_e32 v0, v183, v0, vcc
	v_lshlrev_b32_e32 v42, 2, v0
	v_xor_b32_e32 v0, 4, v183
	v_cmp_lt_i32_e32 vcc, v0, v1
	v_mov_b32_e32 v53, 0
	s_nop 0
	v_cndmask_b32_e32 v0, v183, v0, vcc
	v_lshlrev_b32_e32 v43, 2, v0
	s_branch .LBB0_393
.LBB0_392:
	s_or_b64 exec, exec, s[0:1]
	s_waitcnt vmcnt(0)
	v_lshlrev_b32_e32 v55, 16, v32
	v_and_b32_e32 v32, 0xffff0000, v32
	v_mul_f32_e32 v32, v32, v32
	v_lshlrev_b32_e32 v56, 16, v33
	v_fmac_f32_e32 v32, v55, v55
	v_and_b32_e32 v33, 0xffff0000, v33
	v_fmac_f32_e32 v32, v56, v56
	v_lshlrev_b32_e32 v57, 16, v34
	v_fmac_f32_e32 v32, v33, v33
	v_and_b32_e32 v34, 0xffff0000, v34
	v_fmac_f32_e32 v32, v57, v57
	v_lshlrev_b32_e32 v58, 16, v35
	v_fmac_f32_e32 v32, v34, v34
	v_and_b32_e32 v35, 0xffff0000, v35
	v_fmac_f32_e32 v32, v58, v58
	v_fmac_f32_e32 v32, v35, v35
	ds_bpermute_b32 v33, v41, v32
	v_max_f32_e32 v34, v52, v52
	v_lshlrev_b32_e32 v35, 16, v29
	v_cmp_lt_i32_e32 vcc, s9, v54
	v_and_b32_e32 v29, 0xffff0000, v29
	s_waitcnt lgkmcnt(0)
	v_add_f32_e32 v32, v32, v33
	ds_bpermute_b32 v33, v42, v32
	s_add_i32 s0, s101, s101
	s_add_i32 s0, s0, s0
	s_add_i32 s0, s0, s0
	v_add_u32_e32 v54, s0, v44
	s_waitcnt lgkmcnt(0)
	v_add_f32_e32 v32, v32, v33
	ds_bpermute_b32 v33, v43, v32
	s_movk_i32 s0, 0x40ff
	s_waitcnt lgkmcnt(0)
	v_add_f32_e32 v32, v32, v33
	v_max_f32_e32 v33, v53, v53
	v_max_f32_e32 v33, v33, v32
	v_max_f32_e32 v32, v34, v32
	v_lshlrev_b32_e32 v34, 16, v28
	v_and_b32_e32 v28, 0xffff0000, v28
	v_mul_f32_e32 v28, v28, v28
	v_fmac_f32_e32 v28, v34, v34
	v_fmac_f32_e32 v28, v35, v35
	v_cndmask_b32_e32 v32, v32, v52, vcc
	v_lshlrev_b32_e32 v52, 16, v30
	v_fmac_f32_e32 v28, v29, v29
	v_and_b32_e32 v30, 0xffff0000, v30
	v_fmac_f32_e32 v28, v52, v52
	v_cndmask_b32_e32 v33, v53, v33, vcc
	v_lshlrev_b32_e32 v53, 16, v31
	v_fmac_f32_e32 v28, v30, v30
	v_and_b32_e32 v31, 0xffff0000, v31
	v_fmac_f32_e32 v28, v53, v53
	v_fmac_f32_e32 v28, v31, v31
	ds_bpermute_b32 v29, v41, v28
	v_max_f32_e32 v30, v32, v32
	v_cmp_lt_i32_e32 vcc, s9, v44
	v_lshlrev_b32_e32 v31, 16, v25
	v_and_b32_e32 v25, 0xffff0000, v25
	s_waitcnt lgkmcnt(0)
	v_add_f32_e32 v28, v28, v29
	ds_bpermute_b32 v29, v42, v28
	s_waitcnt lgkmcnt(0)
	v_add_f32_e32 v28, v28, v29
	ds_bpermute_b32 v29, v43, v28
	s_waitcnt lgkmcnt(0)
	v_add_f32_e32 v28, v28, v29
	v_max_f32_e32 v29, v33, v33
	v_max_f32_e32 v29, v29, v28
	v_max_f32_e32 v28, v30, v28
	v_lshlrev_b32_e32 v30, 16, v24
	v_and_b32_e32 v24, 0xffff0000, v24
	v_cndmask_b32_e32 v29, v33, v29, vcc
	v_mul_f32_e32 v33, v24, v24
	v_fmac_f32_e32 v33, v30, v30
	v_fmac_f32_e32 v33, v31, v31
	v_cndmask_b32_e32 v28, v28, v32, vcc
	v_lshlrev_b32_e32 v32, 16, v26
	v_fmac_f32_e32 v33, v25, v25
	v_and_b32_e32 v26, 0xffff0000, v26
	v_fmac_f32_e32 v33, v32, v32
	v_and_b32_e32 v24, 0xffff0000, v27
	v_lshlrev_b32_e32 v25, 16, v27
	v_fmac_f32_e32 v33, v26, v26
	v_pk_mul_f32 v[24:25], v[24:25], v[24:25]
	v_max_f32_e32 v26, v28, v28
	v_add_f32_e32 v25, v25, v33
	v_add_f32_e32 v24, v24, v25
	ds_bpermute_b32 v25, v41, v24
	v_cmp_lt_i32_e32 vcc, s9, v51
	v_lshlrev_b32_e32 v27, 16, v21
	v_and_b32_e32 v21, 0xffff0000, v21
	s_waitcnt lgkmcnt(0)
	v_add_f32_e32 v24, v24, v25
	ds_bpermute_b32 v25, v42, v24
	s_waitcnt lgkmcnt(0)
	v_add_f32_e32 v24, v24, v25
	ds_bpermute_b32 v25, v43, v24
	s_waitcnt lgkmcnt(0)
	v_add_f32_e32 v24, v24, v25
	v_max_f32_e32 v25, v29, v29
	v_max_f32_e32 v25, v25, v24
	v_max_f32_e32 v24, v26, v24
	v_lshlrev_b32_e32 v26, 16, v20
	v_and_b32_e32 v20, 0xffff0000, v20
	v_cndmask_b32_e32 v25, v29, v25, vcc
	v_mul_f32_e32 v29, v20, v20
	v_fmac_f32_e32 v29, v26, v26
	v_fmac_f32_e32 v29, v27, v27
	v_cndmask_b32_e32 v24, v24, v28, vcc
	v_lshlrev_b32_e32 v28, 16, v22
	v_fmac_f32_e32 v29, v21, v21
	v_and_b32_e32 v22, 0xffff0000, v22
	v_fmac_f32_e32 v29, v28, v28
	v_and_b32_e32 v20, 0xffff0000, v23
	v_lshlrev_b32_e32 v21, 16, v23
	v_fmac_f32_e32 v29, v22, v22
	v_pk_mul_f32 v[20:21], v[20:21], v[20:21]
	v_max_f32_e32 v22, v24, v24
	v_add_f32_e32 v21, v21, v29
	v_add_f32_e32 v20, v20, v21
	ds_bpermute_b32 v21, v41, v20
	v_cmp_lt_i32_e32 vcc, s9, v50
	v_lshlrev_b32_e32 v23, 16, v17
	v_and_b32_e32 v17, 0xffff0000, v17
	s_waitcnt lgkmcnt(0)
	v_add_f32_e32 v20, v20, v21
	ds_bpermute_b32 v21, v42, v20
	s_waitcnt lgkmcnt(0)
	v_add_f32_e32 v20, v20, v21
	ds_bpermute_b32 v21, v43, v20
	s_waitcnt lgkmcnt(0)
	v_add_f32_e32 v20, v20, v21
	v_max_f32_e32 v21, v25, v25
	v_max_f32_e32 v21, v21, v20
	v_max_f32_e32 v20, v22, v20
	v_lshlrev_b32_e32 v22, 16, v16
	v_and_b32_e32 v16, 0xffff0000, v16
	v_cndmask_b32_e32 v20, v20, v24, vcc
	v_mul_f32_e32 v24, v16, v16
	v_fmac_f32_e32 v24, v22, v22
	v_fmac_f32_e32 v24, v23, v23
	v_fmac_f32_e32 v24, v17, v17
	v_and_b32_e32 v16, 0xffff0000, v18
	v_lshlrev_b32_e32 v17, 16, v18
	v_pk_mul_f32 v[16:17], v[16:17], v[16:17]
	v_cndmask_b32_e32 v21, v25, v21, vcc
	v_add_f32_e32 v17, v17, v24
	v_add_f32_e32 v18, v16, v17
	v_and_b32_e32 v16, 0xffff0000, v19
	v_lshlrev_b32_e32 v17, 16, v19
	v_pk_mul_f32 v[16:17], v[16:17], v[16:17]
	v_cmp_lt_i32_e32 vcc, s9, v49
	v_add_f32_e32 v17, v17, v18
	v_add_f32_e32 v16, v16, v17
	ds_bpermute_b32 v17, v41, v16
	v_max_f32_e32 v18, v20, v20
	v_lshlrev_b32_e32 v19, 16, v13
	v_and_b32_e32 v13, 0xffff0000, v13
	s_waitcnt lgkmcnt(0)
	v_add_f32_e32 v16, v16, v17
	ds_bpermute_b32 v17, v42, v16
	s_waitcnt lgkmcnt(0)
	v_add_f32_e32 v16, v16, v17
	ds_bpermute_b32 v17, v43, v16
	s_waitcnt lgkmcnt(0)
	v_add_f32_e32 v16, v16, v17
	v_max_f32_e32 v17, v21, v21
	v_max_f32_e32 v17, v17, v16
	v_max_f32_e32 v16, v18, v16
	v_lshlrev_b32_e32 v18, 16, v12
	v_and_b32_e32 v12, 0xffff0000, v12
	v_cndmask_b32_e32 v16, v16, v20, vcc
	v_mul_f32_e32 v20, v12, v12
	v_fmac_f32_e32 v20, v18, v18
	v_fmac_f32_e32 v20, v19, v19
	v_fmac_f32_e32 v20, v13, v13
	v_and_b32_e32 v12, 0xffff0000, v14
	v_lshlrev_b32_e32 v13, 16, v14
	v_pk_mul_f32 v[12:13], v[12:13], v[12:13]
	v_cndmask_b32_e32 v17, v21, v17, vcc
	v_add_f32_e32 v13, v13, v20
	v_add_f32_e32 v14, v12, v13
	v_and_b32_e32 v12, 0xffff0000, v15
	v_lshlrev_b32_e32 v13, 16, v15
	v_pk_mul_f32 v[12:13], v[12:13], v[12:13]
	v_cmp_lt_i32_e32 vcc, s9, v48
	v_add_f32_e32 v13, v13, v14
	v_add_f32_e32 v12, v12, v13
	ds_bpermute_b32 v13, v41, v12
	v_max_f32_e32 v14, v16, v16
	s_waitcnt lgkmcnt(0)
	v_add_f32_e32 v12, v12, v13
	ds_bpermute_b32 v13, v42, v12
	s_waitcnt lgkmcnt(0)
	v_add_f32_e32 v12, v12, v13
	ds_bpermute_b32 v13, v43, v12
	s_waitcnt lgkmcnt(0)
	v_add_f32_e32 v12, v12, v13
	v_max_f32_e32 v13, v17, v17
	v_max_f32_e32 v13, v13, v12
	v_max_f32_e32 v12, v14, v12
	v_lshlrev_b32_e32 v14, 16, v8
	v_and_b32_e32 v8, 0xffff0000, v8
	v_mul_f32_e32 v15, v8, v8
	v_and_b32_e32 v8, 0xffff0000, v9
	v_lshlrev_b32_e32 v9, 16, v9
	v_fmac_f32_e32 v15, v14, v14
	v_pk_mul_f32 v[8:9], v[8:9], v[8:9]
	v_cndmask_b32_e32 v13, v17, v13, vcc
	v_add_f32_e32 v9, v9, v15
	v_add_f32_e32 v14, v8, v9
	v_and_b32_e32 v8, 0xffff0000, v10
	v_lshlrev_b32_e32 v9, 16, v10
	v_pk_mul_f32 v[8:9], v[8:9], v[8:9]
	v_cndmask_b32_e32 v12, v12, v16, vcc
	v_add_f32_e32 v9, v9, v14
	v_add_f32_e32 v10, v8, v9
	v_and_b32_e32 v8, 0xffff0000, v11
	v_lshlrev_b32_e32 v9, 16, v11
	v_pk_mul_f32 v[8:9], v[8:9], v[8:9]
	v_cmp_lt_i32_e32 vcc, s9, v47
	v_add_f32_e32 v9, v9, v10
	v_add_f32_e32 v8, v8, v9
	ds_bpermute_b32 v9, v41, v8
	v_max_f32_e32 v10, v12, v12
	s_waitcnt lgkmcnt(0)
	v_add_f32_e32 v8, v8, v9
	ds_bpermute_b32 v9, v42, v8
	s_waitcnt lgkmcnt(0)
	v_add_f32_e32 v8, v8, v9
	ds_bpermute_b32 v9, v43, v8
	s_waitcnt lgkmcnt(0)
	v_add_f32_e32 v8, v8, v9
	v_max_f32_e32 v9, v13, v13
	v_max_f32_e32 v9, v9, v8
	v_max_f32_e32 v8, v10, v8
	v_lshlrev_b32_e32 v10, 16, v4
	v_and_b32_e32 v4, 0xffff0000, v4
	v_mul_f32_e32 v11, v4, v4
	v_and_b32_e32 v4, 0xffff0000, v5
	v_lshlrev_b32_e32 v5, 16, v5
	v_fmac_f32_e32 v11, v10, v10
	v_pk_mul_f32 v[4:5], v[4:5], v[4:5]
	v_cndmask_b32_e32 v9, v13, v9, vcc
	v_add_f32_e32 v5, v5, v11
	v_add_f32_e32 v10, v4, v5
	v_and_b32_e32 v4, 0xffff0000, v6
	v_lshlrev_b32_e32 v5, 16, v6
	v_pk_mul_f32 v[4:5], v[4:5], v[4:5]
	v_cndmask_b32_e32 v8, v8, v12, vcc
	v_add_f32_e32 v5, v5, v10
	v_add_f32_e32 v6, v4, v5
	v_and_b32_e32 v4, 0xffff0000, v7
	v_lshlrev_b32_e32 v5, 16, v7
	v_pk_mul_f32 v[4:5], v[4:5], v[4:5]
	v_cmp_lt_i32_e32 vcc, s9, v46
	v_add_f32_e32 v5, v5, v6
	v_add_f32_e32 v4, v4, v5
	ds_bpermute_b32 v5, v41, v4
	v_max_f32_e32 v6, v8, v8
	v_lshlrev_b32_e32 v7, 16, v2
	s_waitcnt lgkmcnt(0)
	v_add_f32_e32 v4, v4, v5
	ds_bpermute_b32 v5, v42, v4
	s_waitcnt lgkmcnt(0)
	v_add_f32_e32 v4, v4, v5
	ds_bpermute_b32 v5, v43, v4
	s_waitcnt lgkmcnt(0)
	v_add_f32_e32 v4, v4, v5
	v_max_f32_e32 v5, v9, v9
	v_max_f32_e32 v5, v5, v4
	v_max_f32_e32 v4, v6, v4
	v_cndmask_b32_e32 v9, v9, v5, vcc
	v_cndmask_b32_e32 v8, v4, v8, vcc
	v_lshlrev_b32_e32 v4, 16, v0
	v_and_b32_e32 v5, 0xffff0000, v0
	v_pk_mul_f32 v[4:5], v[4:5], v[4:5]
	v_and_b32_e32 v0, 0xffff0000, v1
	v_lshlrev_b32_e32 v1, 16, v1
	v_pk_mul_f32 v[0:1], v[0:1], v[0:1]
	v_add_f32_e32 v4, v4, v5
	v_and_b32_e32 v6, 0xffff0000, v2
	v_add_f32_e32 v1, v1, v4
	v_pk_mul_f32 v[6:7], v[6:7], v[6:7]
	v_add_f32_e32 v0, v0, v1
	v_and_b32_e32 v2, 0xffff0000, v3
	v_lshlrev_b32_e32 v3, 16, v3
	v_add_f32_e32 v0, v7, v0
	v_pk_mul_f32 v[2:3], v[2:3], v[2:3]
	v_add_f32_e32 v0, v6, v0
	v_add_f32_e32 v0, v3, v0
	v_add_f32_e32 v0, v2, v0
	ds_bpermute_b32 v1, v41, v0
	v_max_f32_e32 v2, v8, v8
	v_cmp_lt_i32_e32 vcc, s9, v45
	s_waitcnt lgkmcnt(0)
	v_add_f32_e32 v0, v0, v1
	ds_bpermute_b32 v1, v42, v0
	s_waitcnt lgkmcnt(0)
	v_add_f32_e32 v0, v0, v1
	ds_bpermute_b32 v1, v43, v0
	s_waitcnt lgkmcnt(0)
	v_add_f32_e32 v0, v0, v1
	v_max_f32_e32 v1, v9, v9
	v_max_f32_e32 v1, v1, v0
	v_max_f32_e32 v0, v2, v0
	v_cndmask_b32_e32 v53, v9, v1, vcc
	v_cndmask_b32_e32 v52, v0, v8, vcc
	v_cmp_lt_i32_e32 vcc, s0, v54
	s_or_b64 s[36:37], vcc, s[36:37]
	s_andn2_b64 exec, exec, s[36:37]
	s_cbranch_execz .LBB0_409
.LBB0_393:
	v_mad_i64_i32 v[0:1], s[0:1], v54, s22, v[38:39]
	global_load_dwordx4 v[32:35], v[0:1], off offset:1024
	v_add_u32_e32 v44, s101, v54
	v_cmp_gt_i32_e32 vcc, s23, v44
	v_mov_b32_e32 v28, 0
	v_mov_b32_e32 v29, 0
	v_mov_b32_e32 v30, 0
	v_mov_b32_e32 v31, 0
	s_and_saveexec_b64 s[0:1], vcc
	s_cbranch_execz .LBB0_395
	v_mad_i64_i32 v[0:1], s[20:21], v44, s22, v[38:39]
	global_load_dwordx4 v[28:31], v[0:1], off offset:1024
.LBB0_395:
	s_or_b64 exec, exec, s[0:1]
	s_lshl_b32 s0, s101, 1
	v_add_u32_e32 v51, s0, v54
	v_cmp_gt_i32_e32 vcc, s23, v51
	v_mov_b32_e32 v20, 0
	v_mov_b32_e32 v24, 0
	v_mov_b32_e32 v25, 0
	v_mov_b32_e32 v26, 0
	v_mov_b32_e32 v27, 0
	s_and_saveexec_b64 s[0:1], vcc
	s_cbranch_execz .LBB0_397
	v_mad_i64_i32 v[0:1], s[20:21], v51, s22, v[38:39]
	global_load_dwordx4 v[24:27], v[0:1], off offset:1024
.LBB0_397:
	s_or_b64 exec, exec, s[0:1]
	s_mul_i32 s0, s101, 3
	v_add_u32_e32 v50, s0, v54
	v_cmp_gt_i32_e32 vcc, s23, v50
	v_mov_b32_e32 v21, 0
	v_mov_b32_e32 v22, 0
	v_mov_b32_e32 v23, 0
	s_and_saveexec_b64 s[0:1], vcc
	s_cbranch_execz .LBB0_399
	v_mad_i64_i32 v[0:1], s[20:21], v50, s22, v[38:39]
	global_load_dwordx4 v[20:23], v[0:1], off offset:1024
.LBB0_399:
	s_or_b64 exec, exec, s[0:1]
	s_lshl_b32 s0, s101, 2
	v_add_u32_e32 v49, s0, v54
	v_cmp_gt_i32_e32 vcc, s23, v49
	v_mov_b32_e32 v12, 0
	v_mov_b32_e32 v16, 0
	v_mov_b32_e32 v17, 0
	v_mov_b32_e32 v18, 0
	v_mov_b32_e32 v19, 0
	s_and_saveexec_b64 s[0:1], vcc
	s_cbranch_execz .LBB0_401
	v_mad_i64_i32 v[0:1], s[20:21], v49, s22, v[38:39]
	global_load_dwordx4 v[16:19], v[0:1], off offset:1024
.LBB0_401:
	s_or_b64 exec, exec, s[0:1]
	s_mul_i32 s0, s101, 5
	v_add_u32_e32 v48, s0, v54
	v_cmp_gt_i32_e32 vcc, s23, v48
	v_mov_b32_e32 v13, 0
	v_mov_b32_e32 v14, 0
	v_mov_b32_e32 v15, 0
	s_and_saveexec_b64 s[0:1], vcc
	s_cbranch_execz .LBB0_403
	v_mad_i64_i32 v[0:1], s[20:21], v48, s22, v[38:39]
	global_load_dwordx4 v[12:15], v[0:1], off offset:1024
.LBB0_403:
	s_or_b64 exec, exec, s[0:1]
	s_mul_i32 s0, s101, 6
	v_add_u32_e32 v47, s0, v54
	v_cmp_gt_i32_e32 vcc, s23, v47
	v_mov_b32_e32 v4, 0
	v_mov_b32_e32 v8, 0
	v_mov_b32_e32 v9, 0
	v_mov_b32_e32 v10, 0
	v_mov_b32_e32 v11, 0
	s_and_saveexec_b64 s[0:1], vcc
	s_cbranch_execz .LBB0_405
	v_mad_i64_i32 v[0:1], s[20:21], v47, s22, v[38:39]
	global_load_dwordx4 v[8:11], v[0:1], off offset:1024
.LBB0_405:
	s_or_b64 exec, exec, s[0:1]
	s_mul_i32 s0, s101, 7
	v_add_u32_e32 v46, s0, v54
	v_cmp_gt_i32_e32 vcc, s23, v46
	v_mov_b32_e32 v5, 0
	v_mov_b32_e32 v6, 0
	v_mov_b32_e32 v7, 0
	s_and_saveexec_b64 s[0:1], vcc
	s_cbranch_execz .LBB0_407
	v_mad_i64_i32 v[0:1], s[20:21], v46, s22, v[38:39]
	global_load_dwordx4 v[4:7], v[0:1], off offset:1024
.LBB0_407:
	s_or_b64 exec, exec, s[0:1]
	s_lshl_b32 s0, s101, 3
	v_mov_b32_e32 v0, 0
	v_mov_b32_e32 v1, 0
	v_add_u32_e32 v45, s0, v54
	v_cmp_gt_i32_e32 vcc, s23, v45
	v_mov_b32_e32 v2, 0
	v_mov_b32_e32 v3, 0
	s_and_saveexec_b64 s[0:1], vcc
	s_cbranch_execz .LBB0_392
	v_mad_i64_i32 v[0:1], s[20:21], v45, s22, v[38:39]
	global_load_dwordx4 v[0:3], v[0:1], off offset:1024
	s_branch .LBB0_392
